# NSA block-importance sums: 8 serialized <=5-trip LDS read/add loops unrolled with batched reads (same add order)
# speedup vs baseline: 1.0031x; 1.0026x over previous
; #define LAS __attribute__((address_space(3)))
; __device__ __forceinline__ float sigmoidf_(float x) { return 1.f / (1.f + __expf(-x)); }
; __device__ __forceinline__ void nsa_attn_cmp(const Ctx& c, const bf16* Q, const bf16* KCb, const bf16* VCT, const float* Gt, float* NACC, unsigned long long* SMg) {
;     ...
;           for (int mi = 0; mi < 2; ++mi) { const float g0 = sigmoidf_(Gt[(size_t)grow[mi] * 48 + (hcol[mi] >> 7) * 3 + 0]);
; #pragma unroll
;               for (int dt = 0; dt < 8; ++dt) *(f32x4*)(NACC + (size_t)grow[mi] * 2048 + hcol[mi] + 16 * dt + 4 * lg) = O[dt][mi] * g0; }
;         }
;         __syncthreads();
;         for (int i = 0; i < 8; ++i) { const int tl = 8 * c.wave + i; const LAS float* pr = PS + tl * fa::PS_STRIDE; float imp = 0.f;
;             { const int i0 = (4 * lane - 1) < 0 ? 0 : 4 * lane - 1; int i1 = (4 * lane + 3) > 254 ? 254 : 4 * lane + 3; if (i1 > 64 * ntile - 1) i1 = 64 * ntile - 1; for (int q = i0; q <= i1; ++q) imp += pr[q]; }
.LBB0_2186:
	v_mul_u32_u24_e32 v8, 3, v163
	v_mov_b64_e32 v[6:7], s[16:17]
	v_mad_i64_i32 v[4:5], s[6:7], v172, s39, v[6:7]
	v_lshlrev_b32_e32 v148, 2, v8
	v_lshl_add_u64 v[4:5], v[4:5], 0, v[148:149]
	global_load_dword v4, v[4:5], off
	v_readlane_b32 s8, v254, 10
	v_readlane_b32 s9, v254, 11
	v_mov_b32_e32 v163, v149
	v_mad_i64_i32 v[6:7], s[6:7], v168, s39, v[6:7]
	v_lshl_add_u64 v[6:7], v[6:7], 0, v[148:149]
	s_waitcnt vmcnt(0)
	v_mul_f32_e32 v4, 0xbfb8aa3b, v4
	v_exp_f32_e32 v4, v4
	s_nop 0
	v_add_f32_e32 v4, 1.0, v4
	v_div_scale_f32 v5, s[6:7], v4, v4, 1.0
	v_rcp_f32_e32 v8, v5
	s_nop 0
	v_fma_f32 v9, -v5, v8, 1.0
	v_fmac_f32_e32 v8, v9, v8
	v_div_scale_f32 v9, vcc, 1.0, v4, 1.0
	v_mul_f32_e32 v10, v9, v8
	v_fma_f32 v11, -v5, v10, v9
	v_fmac_f32_e32 v10, v11, v8
	v_fma_f32 v5, -v5, v10, v9
	v_div_fmas_f32 v5, v5, v8, v10
	v_div_fixup_f32 v12, v5, v4, 1.0
	v_lshlrev_b64 v[4:5], 13, v[172:173]
	v_lshl_add_u64 v[8:9], s[8:9], 0, v[4:5]
	v_lshlrev_b32_e32 v4, 2, v170
	v_mov_b32_e32 v5, v149
	v_lshl_add_u64 v[8:9], v[8:9], 0, v[4:5]
	v_lshl_add_u64 v[14:15], v[8:9], 0, v[162:163]
	v_pk_mul_f32 v[10:11], v[114:115], v[12:13] op_sel_hi:[1,0]
	v_pk_mul_f32 v[8:9], v[112:113], v[12:13] op_sel_hi:[1,0]
	global_store_dwordx4 v[14:15], v[8:11], off
	s_nop 1
	v_pk_mul_f32 v[10:11], v[110:111], v[12:13] op_sel_hi:[1,0]
	v_pk_mul_f32 v[8:9], v[108:109], v[12:13] op_sel_hi:[1,0]
	global_store_dwordx4 v[14:15], v[8:11], off offset:64
	s_nop 1
	v_pk_mul_f32 v[10:11], v[106:107], v[12:13] op_sel_hi:[1,0]
	v_pk_mul_f32 v[8:9], v[104:105], v[12:13] op_sel_hi:[1,0]
	global_store_dwordx4 v[14:15], v[8:11], off offset:128
	s_nop 1
	v_pk_mul_f32 v[10:11], v[102:103], v[12:13] op_sel_hi:[1,0]
	v_pk_mul_f32 v[8:9], v[100:101], v[12:13] op_sel_hi:[1,0]
	global_store_dwordx4 v[14:15], v[8:11], off offset:192
	s_nop 1
	v_pk_mul_f32 v[10:11], v[98:99], v[12:13] op_sel_hi:[1,0]
	v_pk_mul_f32 v[8:9], v[96:97], v[12:13] op_sel_hi:[1,0]
	global_store_dwordx4 v[14:15], v[8:11], off offset:256
	s_nop 1
	v_pk_mul_f32 v[10:11], v[94:95], v[12:13] op_sel_hi:[1,0]
	v_pk_mul_f32 v[8:9], v[92:93], v[12:13] op_sel_hi:[1,0]
	global_store_dwordx4 v[14:15], v[8:11], off offset:320
	s_nop 1
	v_pk_mul_f32 v[10:11], v[74:75], v[12:13] op_sel_hi:[1,0]
	v_pk_mul_f32 v[8:9], v[72:73], v[12:13] op_sel_hi:[1,0]
	global_store_dwordx4 v[14:15], v[8:11], off offset:384
	s_nop 1
	v_pk_mul_f32 v[10:11], v[70:71], v[12:13] op_sel_hi:[1,0]
	v_pk_mul_f32 v[8:9], v[68:69], v[12:13] op_sel_hi:[1,0]
	global_store_dwordx4 v[14:15], v[8:11], off offset:448
	global_load_dword v6, v[6:7], off
	s_waitcnt vmcnt(0)
	v_mul_f32_e32 v6, 0xbfb8aa3b, v6
	v_exp_f32_e32 v6, v6
	s_nop 0
	v_add_f32_e32 v6, 1.0, v6
	v_div_scale_f32 v7, s[6:7], v6, v6, 1.0
	v_rcp_f32_e32 v8, v7
	s_and_b32 s6, s42, 0x7fffffc0
	s_add_i32 s6, s6, -1
	v_fma_f32 v9, -v7, v8, 1.0
	v_fmac_f32_e32 v8, v9, v8
	v_div_scale_f32 v9, vcc, 1.0, v6, 1.0
	v_mul_f32_e32 v10, v9, v8
	v_fma_f32 v11, -v7, v10, v9
	v_fmac_f32_e32 v10, v11, v8
	v_fma_f32 v7, -v7, v10, v9
	v_div_fmas_f32 v7, v7, v8, v10
	v_div_fixup_f32 v8, v7, v6, 1.0
	v_lshlrev_b64 v[6:7], 13, v[168:169]
	v_lshl_add_u64 v[6:7], s[8:9], 0, v[6:7]
	v_lshl_add_u64 v[4:5], v[6:7], 0, v[4:5]
	v_lshl_add_u64 v[10:11], v[4:5], 0, v[162:163]
	v_pk_mul_f32 v[6:7], v[66:67], v[8:9] op_sel_hi:[1,0]
	v_pk_mul_f32 v[4:5], v[64:65], v[8:9] op_sel_hi:[1,0]
	global_store_dwordx4 v[10:11], v[4:7], off
	s_nop 1
	v_pk_mul_f32 v[6:7], v[62:63], v[8:9] op_sel_hi:[1,0]
	v_pk_mul_f32 v[4:5], v[60:61], v[8:9] op_sel_hi:[1,0]
	global_store_dwordx4 v[10:11], v[4:7], off offset:64
	s_nop 1
	v_pk_mul_f32 v[6:7], v[58:59], v[8:9] op_sel_hi:[1,0]
	v_pk_mul_f32 v[4:5], v[56:57], v[8:9] op_sel_hi:[1,0]
	global_store_dwordx4 v[10:11], v[4:7], off offset:128
	s_nop 1
	v_pk_mul_f32 v[6:7], v[54:55], v[8:9] op_sel_hi:[1,0]
	v_pk_mul_f32 v[4:5], v[52:53], v[8:9] op_sel_hi:[1,0]
	global_store_dwordx4 v[10:11], v[4:7], off offset:192
	s_nop 1
	v_pk_mul_f32 v[6:7], v[50:51], v[8:9] op_sel_hi:[1,0]
	v_pk_mul_f32 v[4:5], v[48:49], v[8:9] op_sel_hi:[1,0]
	global_store_dwordx4 v[10:11], v[4:7], off offset:256
	s_nop 1
	v_pk_mul_f32 v[6:7], v[46:47], v[8:9] op_sel_hi:[1,0]
	v_pk_mul_f32 v[4:5], v[44:45], v[8:9] op_sel_hi:[1,0]
	global_store_dwordx4 v[10:11], v[4:7], off offset:320
	s_nop 1
	v_pk_mul_f32 v[6:7], v[42:43], v[8:9] op_sel_hi:[1,0]
	v_pk_mul_f32 v[4:5], v[40:41], v[8:9] op_sel_hi:[1,0]
	global_store_dwordx4 v[10:11], v[4:7], off offset:384
	s_nop 1
	v_pk_mul_f32 v[6:7], v[38:39], v[8:9] op_sel_hi:[1,0]
	v_pk_mul_f32 v[4:5], v[36:37], v[8:9] op_sel_hi:[1,0]
	global_store_dwordx4 v[10:11], v[4:7], off offset:448
	s_barrier
	s_nop 0
	v_min3_i32 v4, v199, s6, v225
	v_cmp_le_i32_e32 vcc, v198, v4
	v_mov_b32_e32 v5, 0
	s_and_saveexec_b64 s[8:9], vcc
	s_cbranch_execz .LBB0_2190
	v_mov_b32_e32 v5, 0
	s_mov_b64 s[10:11], 0
	s_waitcnt lgkmcnt(0)
	ds_read_b32 v8, v215
	ds_read_b32 v12, v215 offset:4
	ds_read_b32 v13, v215 offset:8
	ds_read_b32 v14, v215 offset:12
	ds_read_b32 v15, v215 offset:16
	v_add_u32_e32 v7, 1, v214
	v_add_u32_e32 v6, 2, v214
	s_waitcnt lgkmcnt(4)
	v_add_f32_e32 v5, v5, v8
	v_cmp_lt_i32_e64 s[10:11], v7, v4
	s_waitcnt lgkmcnt(3)
	v_add_f32_e32 v17, v5, v12
	s_nop 0
	v_cndmask_b32_e64 v5, v5, v17, s[10:11]
	v_cmp_lt_i32_e64 s[10:11], v6, v4
	v_add_u32_e32 v7, 3, v214
	s_waitcnt lgkmcnt(2)
	v_add_f32_e32 v17, v5, v13
	v_cndmask_b32_e64 v5, v5, v17, s[10:11]
	v_cmp_lt_i32_e64 s[10:11], v7, v4
	v_add_u32_e32 v6, 4, v214
	s_waitcnt lgkmcnt(1)
	v_add_f32_e32 v17, v5, v14
	v_cndmask_b32_e64 v5, v5, v17, s[10:11]
	v_cmp_lt_i32_e64 s[10:11], v6, v4
	s_waitcnt lgkmcnt(0)
	v_add_f32_e32 v17, v5, v15
	s_nop 0
	v_cndmask_b32_e64 v5, v5, v17, s[10:11]

; #define LAS __attribute__((address_space(3)))
; __device__ __forceinline__ void nsa_attn_cmp(const Ctx& c, const bf16* Q, const bf16* KCb, const bf16* VCT, const float* Gt, float* NACC, unsigned long long* SMg) {
;     ...
;         for (int i = 0; i < 8; ++i) { const int tl = 8 * c.wave + i; const LAS float* pr = PS + tl * fa::PS_STRIDE; float imp = 0.f;
;             { const int i0 = (4 * lane - 1) < 0 ? 0 : 4 * lane - 1; int i1 = (4 * lane + 3) > 254 ? 254 : 4 * lane + 3; if (i1 > 64 * ntile - 1) i1 = 64 * ntile - 1; for (int q = i0; q <= i1; ++q) imp += pr[q]; }
.LBB0_2194:
	s_or_b64 exec, exec, s[10:11]
	v_mov_b32_e32 v5, 0
	s_and_saveexec_b64 s[12:13], vcc
	s_cbranch_execz .LBB0_2198
	v_mov_b32_e32 v5, 0
	s_mov_b64 s[14:15], 0
	s_waitcnt lgkmcnt(0)
	ds_read_b32 v8, v217
	ds_read_b32 v12, v217 offset:4
	ds_read_b32 v13, v217 offset:8
	ds_read_b32 v14, v217 offset:12
	ds_read_b32 v15, v217 offset:16
	v_add_u32_e32 v7, 1, v214
	v_add_u32_e32 v6, 2, v214
	s_waitcnt lgkmcnt(4)
	v_add_f32_e32 v5, v5, v8
	v_cmp_lt_i32_e64 s[14:15], v7, v4
	s_waitcnt lgkmcnt(3)
	v_add_f32_e32 v17, v5, v12
	s_nop 0
	v_cndmask_b32_e64 v5, v5, v17, s[14:15]
	v_cmp_lt_i32_e64 s[14:15], v6, v4
	v_add_u32_e32 v7, 3, v214
	s_waitcnt lgkmcnt(2)
	v_add_f32_e32 v17, v5, v13
	v_cndmask_b32_e64 v5, v5, v17, s[14:15]
	v_cmp_lt_i32_e64 s[14:15], v7, v4
	v_add_u32_e32 v6, 4, v214
	s_waitcnt lgkmcnt(1)
	v_add_f32_e32 v17, v5, v14
	v_cndmask_b32_e64 v5, v5, v17, s[14:15]
	v_cmp_lt_i32_e64 s[14:15], v6, v4
	s_waitcnt lgkmcnt(0)
	v_add_f32_e32 v17, v5, v15
	s_nop 0
	v_cndmask_b32_e64 v5, v5, v17, s[14:15]

; #define LAS __attribute__((address_space(3)))
; __device__ __forceinline__ void nsa_attn_cmp(const Ctx& c, const bf16* Q, const bf16* KCb, const bf16* VCT, const float* Gt, float* NACC, unsigned long long* SMg) {
;     ...
;         for (int i = 0; i < 8; ++i) { const int tl = 8 * c.wave + i; const LAS float* pr = PS + tl * fa::PS_STRIDE; float imp = 0.f;
;             { const int i0 = (4 * lane - 1) < 0 ? 0 : 4 * lane - 1; int i1 = (4 * lane + 3) > 254 ? 254 : 4 * lane + 3; if (i1 > 64 * ntile - 1) i1 = 64 * ntile - 1; for (int q = i0; q <= i1; ++q) imp += pr[q]; }
.LBB0_2202:
	s_or_b64 exec, exec, s[10:11]
	v_mov_b32_e32 v5, 0
	s_and_saveexec_b64 s[12:13], vcc
	s_cbranch_execz .LBB0_2206
	v_mov_b32_e32 v5, 0
	s_mov_b64 s[14:15], 0
	s_waitcnt lgkmcnt(0)
	ds_read_b32 v8, v218
	ds_read_b32 v12, v218 offset:4
	ds_read_b32 v13, v218 offset:8
	ds_read_b32 v14, v218 offset:12
	ds_read_b32 v15, v218 offset:16
	v_add_u32_e32 v7, 1, v214
	v_add_u32_e32 v6, 2, v214
	s_waitcnt lgkmcnt(4)
	v_add_f32_e32 v5, v5, v8
	v_cmp_lt_i32_e64 s[14:15], v7, v4
	s_waitcnt lgkmcnt(3)
	v_add_f32_e32 v17, v5, v12
	s_nop 0
	v_cndmask_b32_e64 v5, v5, v17, s[14:15]
	v_cmp_lt_i32_e64 s[14:15], v6, v4
	v_add_u32_e32 v7, 3, v214
	s_waitcnt lgkmcnt(2)
	v_add_f32_e32 v17, v5, v13
	v_cndmask_b32_e64 v5, v5, v17, s[14:15]
	v_cmp_lt_i32_e64 s[14:15], v7, v4
	v_add_u32_e32 v6, 4, v214
	s_waitcnt lgkmcnt(1)
	v_add_f32_e32 v17, v5, v14
	v_cndmask_b32_e64 v5, v5, v17, s[14:15]
	v_cmp_lt_i32_e64 s[14:15], v6, v4
	s_waitcnt lgkmcnt(0)
	v_add_f32_e32 v17, v5, v15
	s_nop 0
	v_cndmask_b32_e64 v5, v5, v17, s[14:15]

; #define LAS __attribute__((address_space(3)))
; __device__ __forceinline__ void nsa_attn_cmp(const Ctx& c, const bf16* Q, const bf16* KCb, const bf16* VCT, const float* Gt, float* NACC, unsigned long long* SMg) {
;     ...
;         for (int i = 0; i < 8; ++i) { const int tl = 8 * c.wave + i; const LAS float* pr = PS + tl * fa::PS_STRIDE; float imp = 0.f;
;             { const int i0 = (4 * lane - 1) < 0 ? 0 : 4 * lane - 1; int i1 = (4 * lane + 3) > 254 ? 254 : 4 * lane + 3; if (i1 > 64 * ntile - 1) i1 = 64 * ntile - 1; for (int q = i0; q <= i1; ++q) imp += pr[q]; }
.LBB0_2210:
	s_or_b64 exec, exec, s[10:11]
	v_mov_b32_e32 v5, 0
	s_and_saveexec_b64 s[12:13], vcc
	s_cbranch_execz .LBB0_2214
	v_mov_b32_e32 v5, 0
	s_mov_b64 s[14:15], 0
	s_waitcnt lgkmcnt(0)
	ds_read_b32 v8, v219
	ds_read_b32 v12, v219 offset:4
	ds_read_b32 v13, v219 offset:8
	ds_read_b32 v14, v219 offset:12
	ds_read_b32 v15, v219 offset:16
	v_add_u32_e32 v7, 1, v214
	v_add_u32_e32 v6, 2, v214
	s_waitcnt lgkmcnt(4)
	v_add_f32_e32 v5, v5, v8
	v_cmp_lt_i32_e64 s[14:15], v7, v4
	s_waitcnt lgkmcnt(3)
	v_add_f32_e32 v17, v5, v12
	s_nop 0
	v_cndmask_b32_e64 v5, v5, v17, s[14:15]
	v_cmp_lt_i32_e64 s[14:15], v6, v4
	v_add_u32_e32 v7, 3, v214
	s_waitcnt lgkmcnt(2)
	v_add_f32_e32 v17, v5, v13
	v_cndmask_b32_e64 v5, v5, v17, s[14:15]
	v_cmp_lt_i32_e64 s[14:15], v7, v4
	v_add_u32_e32 v6, 4, v214
	s_waitcnt lgkmcnt(1)
	v_add_f32_e32 v17, v5, v14
	v_cndmask_b32_e64 v5, v5, v17, s[14:15]
	v_cmp_lt_i32_e64 s[14:15], v6, v4
	s_waitcnt lgkmcnt(0)
	v_add_f32_e32 v17, v5, v15
	s_nop 0
	v_cndmask_b32_e64 v5, v5, v17, s[14:15]

; #define LAS __attribute__((address_space(3)))
; __device__ __forceinline__ void nsa_attn_cmp(const Ctx& c, const bf16* Q, const bf16* KCb, const bf16* VCT, const float* Gt, float* NACC, unsigned long long* SMg) {
;     ...
;         for (int i = 0; i < 8; ++i) { const int tl = 8 * c.wave + i; const LAS float* pr = PS + tl * fa::PS_STRIDE; float imp = 0.f;
;             { const int i0 = (4 * lane - 1) < 0 ? 0 : 4 * lane - 1; int i1 = (4 * lane + 3) > 254 ? 254 : 4 * lane + 3; if (i1 > 64 * ntile - 1) i1 = 64 * ntile - 1; for (int q = i0; q <= i1; ++q) imp += pr[q]; }
.LBB0_2218:
	s_or_b64 exec, exec, s[10:11]
	v_mov_b32_e32 v5, 0
	s_and_saveexec_b64 s[12:13], vcc
	s_cbranch_execz .LBB0_2222
	v_mov_b32_e32 v5, 0
	s_mov_b64 s[14:15], 0
	s_waitcnt lgkmcnt(0)
	ds_read_b32 v8, v220
	ds_read_b32 v12, v220 offset:4
	ds_read_b32 v13, v220 offset:8
	ds_read_b32 v14, v220 offset:12
	ds_read_b32 v15, v220 offset:16
	v_add_u32_e32 v7, 1, v214
	v_add_u32_e32 v6, 2, v214
	s_waitcnt lgkmcnt(4)
	v_add_f32_e32 v5, v5, v8
	v_cmp_lt_i32_e64 s[14:15], v7, v4
	s_waitcnt lgkmcnt(3)
	v_add_f32_e32 v17, v5, v12
	s_nop 0
	v_cndmask_b32_e64 v5, v5, v17, s[14:15]
	v_cmp_lt_i32_e64 s[14:15], v6, v4
	v_add_u32_e32 v7, 3, v214
	s_waitcnt lgkmcnt(2)
	v_add_f32_e32 v17, v5, v13
	v_cndmask_b32_e64 v5, v5, v17, s[14:15]
	v_cmp_lt_i32_e64 s[14:15], v7, v4
	v_add_u32_e32 v6, 4, v214
	s_waitcnt lgkmcnt(1)
	v_add_f32_e32 v17, v5, v14
	v_cndmask_b32_e64 v5, v5, v17, s[14:15]
	v_cmp_lt_i32_e64 s[14:15], v6, v4
	s_waitcnt lgkmcnt(0)
	v_add_f32_e32 v17, v5, v15
	s_nop 0
	v_cndmask_b32_e64 v5, v5, v17, s[14:15]

; #define LAS __attribute__((address_space(3)))
; __device__ __forceinline__ void nsa_attn_cmp(const Ctx& c, const bf16* Q, const bf16* KCb, const bf16* VCT, const float* Gt, float* NACC, unsigned long long* SMg) {
;     ...
;         for (int i = 0; i < 8; ++i) { const int tl = 8 * c.wave + i; const LAS float* pr = PS + tl * fa::PS_STRIDE; float imp = 0.f;
;             { const int i0 = (4 * lane - 1) < 0 ? 0 : 4 * lane - 1; int i1 = (4 * lane + 3) > 254 ? 254 : 4 * lane + 3; if (i1 > 64 * ntile - 1) i1 = 64 * ntile - 1; for (int q = i0; q <= i1; ++q) imp += pr[q]; }
.LBB0_2226:
	s_or_b64 exec, exec, s[10:11]
	v_mov_b32_e32 v5, 0
	s_and_saveexec_b64 s[12:13], vcc
	s_cbranch_execz .LBB0_2230
	v_mov_b32_e32 v5, 0
	s_mov_b64 s[14:15], 0
	s_waitcnt lgkmcnt(0)
	ds_read_b32 v8, v221
	ds_read_b32 v12, v221 offset:4
	ds_read_b32 v13, v221 offset:8
	ds_read_b32 v14, v221 offset:12
	ds_read_b32 v15, v221 offset:16
	v_add_u32_e32 v7, 1, v214
	v_add_u32_e32 v6, 2, v214
	s_waitcnt lgkmcnt(4)
	v_add_f32_e32 v5, v5, v8
	v_cmp_lt_i32_e64 s[14:15], v7, v4
	s_waitcnt lgkmcnt(3)
	v_add_f32_e32 v17, v5, v12
	s_nop 0
	v_cndmask_b32_e64 v5, v5, v17, s[14:15]
	v_cmp_lt_i32_e64 s[14:15], v6, v4
	v_add_u32_e32 v7, 3, v214
	s_waitcnt lgkmcnt(2)
	v_add_f32_e32 v17, v5, v13
	v_cndmask_b32_e64 v5, v5, v17, s[14:15]
	v_cmp_lt_i32_e64 s[14:15], v7, v4
	v_add_u32_e32 v6, 4, v214
	s_waitcnt lgkmcnt(1)
	v_add_f32_e32 v17, v5, v14
	v_cndmask_b32_e64 v5, v5, v17, s[14:15]
	v_cmp_lt_i32_e64 s[14:15], v6, v4
	s_waitcnt lgkmcnt(0)
	v_add_f32_e32 v17, v5, v15
	s_nop 0
	v_cndmask_b32_e64 v5, v5, v17, s[14:15]

; #define LAS __attribute__((address_space(3)))
; __device__ __forceinline__ void nsa_attn_cmp(const Ctx& c, const bf16* Q, const bf16* KCb, const bf16* VCT, const float* Gt, float* NACC, unsigned long long* SMg) {
;     ...
;         for (int i = 0; i < 8; ++i) { const int tl = 8 * c.wave + i; const LAS float* pr = PS + tl * fa::PS_STRIDE; float imp = 0.f;
;             { const int i0 = (4 * lane - 1) < 0 ? 0 : 4 * lane - 1; int i1 = (4 * lane + 3) > 254 ? 254 : 4 * lane + 3; if (i1 > 64 * ntile - 1) i1 = 64 * ntile - 1; for (int q = i0; q <= i1; ++q) imp += pr[q]; }
.LBB0_2234:
	s_or_b64 exec, exec, s[10:11]
	v_mov_b32_e32 v5, 0
	s_and_saveexec_b64 s[12:13], vcc
	s_cbranch_execz .LBB0_2238
	v_mov_b32_e32 v5, 0
	s_mov_b64 s[14:15], 0
	s_waitcnt lgkmcnt(0)
	ds_read_b32 v8, v222
	ds_read_b32 v12, v222 offset:4
	ds_read_b32 v13, v222 offset:8
	ds_read_b32 v14, v222 offset:12
	ds_read_b32 v15, v222 offset:16
	v_add_u32_e32 v7, 1, v214
	v_add_u32_e32 v6, 2, v214
	s_waitcnt lgkmcnt(4)
	v_add_f32_e32 v5, v5, v8
	v_cmp_lt_i32_e64 s[14:15], v7, v4
	s_waitcnt lgkmcnt(3)
	v_add_f32_e32 v17, v5, v12
	s_nop 0
	v_cndmask_b32_e64 v5, v5, v17, s[14:15]
	v_cmp_lt_i32_e64 s[14:15], v6, v4
	v_add_u32_e32 v7, 3, v214
	s_waitcnt lgkmcnt(2)
	v_add_f32_e32 v17, v5, v13
	v_cndmask_b32_e64 v5, v5, v17, s[14:15]
	v_cmp_lt_i32_e64 s[14:15], v7, v4
	v_add_u32_e32 v6, 4, v214
	s_waitcnt lgkmcnt(1)
	v_add_f32_e32 v17, v5, v14
	v_cndmask_b32_e64 v5, v5, v17, s[14:15]
	v_cmp_lt_i32_e64 s[14:15], v6, v4
	s_waitcnt lgkmcnt(0)
	v_add_f32_e32 v17, v5, v15
	s_nop 0
	v_cndmask_b32_e64 v5, v5, v17, s[14:15]

; #define LAS __attribute__((address_space(3)))
; __device__ __forceinline__ void nsa_attn_cmp(const Ctx& c, const bf16* Q, const bf16* KCb, const bf16* VCT, const float* Gt, float* NACC, unsigned long long* SMg) {
;     ...
;         for (int i = 0; i < 8; ++i) { const int tl = 8 * c.wave + i; const LAS float* pr = PS + tl * fa::PS_STRIDE; float imp = 0.f;
;             { const int i0 = (4 * lane - 1) < 0 ? 0 : 4 * lane - 1; int i1 = (4 * lane + 3) > 254 ? 254 : 4 * lane + 3; if (i1 > 64 * ntile - 1) i1 = 64 * ntile - 1; for (int q = i0; q <= i1; ++q) imp += pr[q]; }
.LBB0_2242:
	s_or_b64 exec, exec, s[10:11]
	v_mov_b32_e32 v5, 0
	s_and_saveexec_b64 s[10:11], vcc
	s_cbranch_execz .LBB0_2246
	v_mov_b32_e32 v5, 0
	s_mov_b64 s[12:13], 0
	s_waitcnt lgkmcnt(0)
	ds_read_b32 v8, v223
	ds_read_b32 v12, v223 offset:4
	ds_read_b32 v13, v223 offset:8
	ds_read_b32 v14, v223 offset:12
	ds_read_b32 v15, v223 offset:16
	v_add_u32_e32 v7, 1, v214
	v_add_u32_e32 v6, 2, v214
	s_waitcnt lgkmcnt(4)
	v_add_f32_e32 v5, v5, v8
	v_cmp_lt_i32_e64 s[12:13], v7, v4
	s_waitcnt lgkmcnt(3)
	v_add_f32_e32 v17, v5, v12
	s_nop 0
	v_cndmask_b32_e64 v5, v5, v17, s[12:13]
	v_cmp_lt_i32_e64 s[12:13], v6, v4
	v_add_u32_e32 v7, 3, v214
	s_waitcnt lgkmcnt(2)
	v_add_f32_e32 v17, v5, v13
	v_cndmask_b32_e64 v5, v5, v17, s[12:13]
	v_cmp_lt_i32_e64 s[12:13], v7, v4
	v_add_u32_e32 v6, 4, v214
	s_waitcnt lgkmcnt(1)
	v_add_f32_e32 v17, v5, v14
	v_cndmask_b32_e64 v5, v5, v17, s[12:13]
	v_cmp_lt_i32_e64 s[12:13], v6, v4
	s_waitcnt lgkmcnt(0)
	v_add_f32_e32 v17, v5, v15
	s_nop 0
	v_cndmask_b32_e64 v5, v5, v17, s[12:13]
